# GEMM1 epilogue: tiles without the per-head norm skip the 35 moves that initialise the (unused) row/column multipliers
# baseline (speedup 1.0000x reference)
.LBB0_203:
	v_mov_b32_e32 v181, 1.0
	v_cndmask_b32_e64 v130, 0, 1, s[34:35]
	v_cmp_ne_u32_e64 s[40:41], 1, v130
	s_andn2_b64 vcc, exec, s[34:35]
	s_cbranch_vccnz .LBB0_237
	v_mov_b32_e32 v180, v181
	v_mov_b32_e32 v185, v181
	v_mov_b32_e32 v184, v181
	v_mov_b32_e32 v189, v181
	v_mov_b32_e32 v188, v181
	v_mov_b32_e32 v193, v181
	v_mov_b32_e32 v192, v181
	v_mov_b32_e32 v169, v181
	v_mov_b32_e32 v168, v181
	v_mov_b32_e32 v183, v181
	v_mov_b32_e32 v182, v181
	v_mov_b32_e32 v187, v181
	v_mov_b32_e32 v186, v181
	v_mov_b32_e32 v191, v181
	v_mov_b32_e32 v190, v181
	v_mov_b32_e32 v175, v181
	v_mov_b32_e32 v174, v181
	v_mov_b32_e32 v173, v181
	v_mov_b32_e32 v172, v181
	v_mov_b32_e32 v163, v181
	v_mov_b32_e32 v162, v181
	v_mov_b32_e32 v161, v181
	v_mov_b32_e32 v160, v181
	v_mov_b32_e32 v165, v181
	v_mov_b32_e32 v164, v181
	v_mov_b32_e32 v167, v181
	v_mov_b32_e32 v166, v181
	v_mov_b32_e32 v171, v181
	v_mov_b32_e32 v170, v181
	v_mov_b32_e32 v177, v181
	v_mov_b32_e32 v176, v181
	s_cbranch_vccnz .LBB0_237
	v_lshl_add_u64 v[228:229], s[42:43], 0, v[146:147]
	v_mov_b32_e32 v230, v156
	v_mov_b32_e32 v231, v147
	v_lshl_add_u64 v[228:229], v[228:229], 0, v[230:231]
	v_bfe_u32 v230, v0, 7, 1
	v_mul_u32_u24_e32 v230, s70, v230
	v_lshlrev_b32_e32 v230, 2, v230
	v_lshl_add_u64 v[228:229], v[228:229], 0, v[230:231]
	global_load_dwordx4 v[200:203], v[228:229], off offset:16
	global_load_dwordx4 v[204:207], v[228:229], off
	v_mov_b32_e32 v230, s70
	v_lshlrev_b32_e32 v230, 3, v230
	v_lshl_add_u64 v[232:233], v[228:229], 0, v[230:231]
	global_load_dwordx4 v[216:219], v[232:233], off offset:16
	global_load_dwordx4 v[224:227], v[232:233], off
	v_pk_mul_f32 v[234:235], v[114:115], v[114:115]
	v_pk_mul_f32 v[236:237], v[98:99], v[98:99]
	v_pk_mul_f32 v[238:239], v[82:83], v[82:83]
	v_pk_mul_f32 v[240:241], v[66:67], v[66:67]
	v_pk_fma_f32 v[234:235], v[116:117], v[116:117], v[234:235]
	v_pk_fma_f32 v[236:237], v[100:101], v[100:101], v[236:237]
	v_pk_fma_f32 v[238:239], v[84:85], v[84:85], v[238:239]
	v_pk_fma_f32 v[240:241], v[68:69], v[68:69], v[240:241]
	v_pk_fma_f32 v[234:235], v[122:123], v[122:123], v[234:235]
	v_pk_fma_f32 v[236:237], v[106:107], v[106:107], v[236:237]
	v_pk_fma_f32 v[238:239], v[90:91], v[90:91], v[238:239]
	v_pk_fma_f32 v[240:241], v[74:75], v[74:75], v[240:241]
	v_pk_fma_f32 v[234:235], v[124:125], v[124:125], v[234:235]
	v_pk_fma_f32 v[236:237], v[108:109], v[108:109], v[236:237]
	v_pk_fma_f32 v[238:239], v[92:93], v[92:93], v[238:239]
	v_pk_fma_f32 v[240:241], v[76:77], v[76:77], v[240:241]
	v_add_f32_e32 v234, v234, v235
	v_add_f32_e32 v236, v236, v237
	v_add_f32_e32 v238, v238, v239
	v_add_f32_e32 v240, v240, v241
	v_mov_b32_e32 v242, v234
	v_mov_b32_e32 v243, v236
	v_mov_b32_e32 v244, v238
	v_mov_b32_e32 v245, v240
	v_permlane16_swap_b32_e32 v242, v234
	v_permlane16_swap_b32_e32 v243, v236
	v_permlane16_swap_b32_e32 v244, v238
	v_permlane16_swap_b32_e32 v245, v240
	v_add_f32_e32 v234, v234, v242
	v_add_f32_e32 v236, v236, v243
	v_add_f32_e32 v238, v238, v244
	v_add_f32_e32 v240, v240, v245
	v_mov_b32_e32 v242, v234
	v_mov_b32_e32 v243, v236
	v_mov_b32_e32 v244, v238
	v_mov_b32_e32 v245, v240
	v_permlane32_swap_b32_e32 v242, v234
	v_permlane32_swap_b32_e32 v243, v236
	v_permlane32_swap_b32_e32 v244, v238
	v_permlane32_swap_b32_e32 v245, v240
	v_add_f32_e32 v132, v234, v242
	v_add_f32_e32 v133, v236, v243
	v_add_f32_e32 v168, v238, v244
	v_add_f32_e32 v169, v240, v245
	s_and_saveexec_b64 s[34:35], s[4:5]
	ds_write_b32 v221, v132
	ds_write_b32 v221, v133 offset:64
	ds_write_b32 v221, v168 offset:128
	ds_write_b32 v221, v169 offset:192
	s_or_b64 exec, exec, s[34:35]
	v_pk_mul_f32 v[234:235], v[50:51], v[50:51]
	v_pk_mul_f32 v[236:237], v[34:35], v[34:35]
	v_pk_mul_f32 v[238:239], v[18:19], v[18:19]
	v_pk_mul_f32 v[240:241], v[2:3], v[2:3]
	v_pk_fma_f32 v[234:235], v[52:53], v[52:53], v[234:235]
	v_pk_fma_f32 v[236:237], v[36:37], v[36:37], v[236:237]
	v_pk_fma_f32 v[238:239], v[20:21], v[20:21], v[238:239]
	v_pk_fma_f32 v[240:241], v[4:5], v[4:5], v[240:241]
	v_pk_fma_f32 v[234:235], v[58:59], v[58:59], v[234:235]
	v_pk_fma_f32 v[236:237], v[42:43], v[42:43], v[236:237]
	v_pk_fma_f32 v[238:239], v[26:27], v[26:27], v[238:239]
	v_pk_fma_f32 v[240:241], v[10:11], v[10:11], v[240:241]
	v_pk_fma_f32 v[234:235], v[60:61], v[60:61], v[234:235]
	v_pk_fma_f32 v[236:237], v[44:45], v[44:45], v[236:237]
	v_pk_fma_f32 v[238:239], v[28:29], v[28:29], v[238:239]
	v_pk_fma_f32 v[240:241], v[12:13], v[12:13], v[240:241]
	v_add_f32_e32 v234, v234, v235
	v_add_f32_e32 v236, v236, v237
	v_add_f32_e32 v238, v238, v239
	v_add_f32_e32 v240, v240, v241
	v_mov_b32_e32 v242, v234
	v_mov_b32_e32 v243, v236
	v_mov_b32_e32 v244, v238
	v_mov_b32_e32 v245, v240
	v_permlane16_swap_b32_e32 v242, v234
	v_permlane16_swap_b32_e32 v243, v236
	v_permlane16_swap_b32_e32 v244, v238
	v_permlane16_swap_b32_e32 v245, v240
	v_add_f32_e32 v234, v234, v242
	v_add_f32_e32 v236, v236, v243
	v_add_f32_e32 v238, v238, v244
	v_add_f32_e32 v240, v240, v245
	v_mov_b32_e32 v242, v234
	v_mov_b32_e32 v243, v236
	v_mov_b32_e32 v244, v238
	v_mov_b32_e32 v245, v240
	v_permlane32_swap_b32_e32 v242, v234
	v_permlane32_swap_b32_e32 v243, v236
	v_permlane32_swap_b32_e32 v244, v238
	v_permlane32_swap_b32_e32 v245, v240
	v_add_f32_e32 v172, v234, v242
	v_add_f32_e32 v173, v236, v243
	v_add_f32_e32 v174, v238, v244
	v_add_f32_e32 v175, v240, v245
	s_and_saveexec_b64 s[34:35], s[4:5]
	ds_write_b32 v254, v172
	ds_write_b32 v221, v173 offset:320
	ds_write_b32 v221, v174 offset:384
	ds_write_b32 v221, v175 offset:448
	s_or_b64 exec, exec, s[34:35]
	v_pk_mul_f32 v[234:235], v[118:119], v[118:119]
	v_pk_mul_f32 v[236:237], v[102:103], v[102:103]
	v_pk_mul_f32 v[238:239], v[86:87], v[86:87]
	v_pk_mul_f32 v[240:241], v[70:71], v[70:71]
	v_pk_fma_f32 v[234:235], v[120:121], v[120:121], v[234:235]
	v_pk_fma_f32 v[236:237], v[104:105], v[104:105], v[236:237]
	v_pk_fma_f32 v[238:239], v[88:89], v[88:89], v[238:239]
	v_pk_fma_f32 v[240:241], v[72:73], v[72:73], v[240:241]
	v_pk_fma_f32 v[234:235], v[126:127], v[126:127], v[234:235]
	v_pk_fma_f32 v[236:237], v[110:111], v[110:111], v[236:237]
	v_pk_fma_f32 v[238:239], v[94:95], v[94:95], v[238:239]
	v_pk_fma_f32 v[240:241], v[78:79], v[78:79], v[240:241]
	v_pk_fma_f32 v[234:235], v[128:129], v[128:129], v[234:235]
	v_pk_fma_f32 v[236:237], v[112:113], v[112:113], v[236:237]
	v_pk_fma_f32 v[238:239], v[96:97], v[96:97], v[238:239]
	v_pk_fma_f32 v[240:241], v[80:81], v[80:81], v[240:241]
	v_add_f32_e32 v234, v234, v235
	v_add_f32_e32 v236, v236, v237
	v_add_f32_e32 v238, v238, v239
	v_add_f32_e32 v240, v240, v241
	v_mov_b32_e32 v242, v234
	v_mov_b32_e32 v243, v236
	v_mov_b32_e32 v244, v238
	v_mov_b32_e32 v245, v240
	v_permlane16_swap_b32_e32 v242, v234
	v_permlane16_swap_b32_e32 v243, v236
	v_permlane16_swap_b32_e32 v244, v238
	v_permlane16_swap_b32_e32 v245, v240
	v_add_f32_e32 v234, v234, v242
	v_add_f32_e32 v236, v236, v243
	v_add_f32_e32 v238, v238, v244
	v_add_f32_e32 v240, v240, v245
	v_mov_b32_e32 v242, v234
	v_mov_b32_e32 v243, v236
	v_mov_b32_e32 v244, v238
	v_mov_b32_e32 v245, v240
	v_permlane32_swap_b32_e32 v242, v234
	v_permlane32_swap_b32_e32 v243, v236
	v_permlane32_swap_b32_e32 v244, v238
	v_permlane32_swap_b32_e32 v245, v240
	v_add_f32_e32 v136, v234, v242
	v_add_f32_e32 v137, v236, v243
	v_add_f32_e32 v158, v238, v244
	v_add_f32_e32 v159, v240, v245
	s_and_saveexec_b64 s[34:35], s[4:5]
	ds_write_b32 v208, v136
	ds_write_b32 v221, v137 offset:576
	ds_write_b32 v221, v158 offset:640
	ds_write_b32 v221, v159 offset:704
	s_or_b64 exec, exec, s[34:35]
	v_pk_mul_f32 v[234:235], v[54:55], v[54:55]
	v_pk_mul_f32 v[236:237], v[38:39], v[38:39]
	v_pk_mul_f32 v[238:239], v[22:23], v[22:23]
	v_pk_mul_f32 v[240:241], v[6:7], v[6:7]
	v_pk_fma_f32 v[234:235], v[56:57], v[56:57], v[234:235]
	v_pk_fma_f32 v[236:237], v[40:41], v[40:41], v[236:237]
	v_pk_fma_f32 v[238:239], v[24:25], v[24:25], v[238:239]
	v_pk_fma_f32 v[240:241], v[8:9], v[8:9], v[240:241]
	v_pk_fma_f32 v[234:235], v[62:63], v[62:63], v[234:235]
	v_pk_fma_f32 v[236:237], v[46:47], v[46:47], v[236:237]
	v_pk_fma_f32 v[238:239], v[30:31], v[30:31], v[238:239]
	v_pk_fma_f32 v[240:241], v[14:15], v[14:15], v[240:241]
	v_pk_fma_f32 v[234:235], v[64:65], v[64:65], v[234:235]
	v_pk_fma_f32 v[236:237], v[48:49], v[48:49], v[236:237]
	v_pk_fma_f32 v[238:239], v[32:33], v[32:33], v[238:239]
	v_pk_fma_f32 v[240:241], v[16:17], v[16:17], v[240:241]
	v_add_f32_e32 v234, v234, v235
	v_add_f32_e32 v236, v236, v237
	v_add_f32_e32 v238, v238, v239
	v_add_f32_e32 v240, v240, v241
	v_mov_b32_e32 v242, v234
	v_mov_b32_e32 v243, v236
	v_mov_b32_e32 v244, v238
	v_mov_b32_e32 v245, v240
	v_permlane16_swap_b32_e32 v242, v234
	v_permlane16_swap_b32_e32 v243, v236
	v_permlane16_swap_b32_e32 v244, v238
	v_permlane16_swap_b32_e32 v245, v240
	v_add_f32_e32 v234, v234, v242
	v_add_f32_e32 v236, v236, v243
	v_add_f32_e32 v238, v238, v244
	v_add_f32_e32 v240, v240, v245
	v_mov_b32_e32 v242, v234
	v_mov_b32_e32 v243, v236
	v_mov_b32_e32 v244, v238
	v_mov_b32_e32 v245, v240
	v_permlane32_swap_b32_e32 v242, v234
	v_permlane32_swap_b32_e32 v243, v236
	v_permlane32_swap_b32_e32 v244, v238
	v_permlane32_swap_b32_e32 v245, v240
	v_add_f32_e32 v134, v234, v242
	v_add_f32_e32 v135, v236, v243
	v_add_f32_e32 v130, v238, v244
	v_add_f32_e32 v131, v240, v245
	s_and_saveexec_b64 s[34:35], s[4:5]
	ds_write_b32 v198, v134
	ds_write_b32 v221, v135 offset:832
	ds_write_b32 v221, v130 offset:896
	ds_write_b32 v196, v131
	s_or_b64 exec, exec, s[34:35]
	s_or_b64 exec, exec, s[34:35]
	v_lshl_add_u64 v[160:161], s[42:43], 0, v[146:147]
	v_mov_b32_e32 v157, v147
	v_lshl_add_u64 v[160:161], v[160:161], 0, v[156:157]
	v_bfe_u32 v157, v0, 7, 1
	v_mul_u32_u24_e32 v157, s70, v157
	v_lshlrev_b32_e32 v162, 2, v157
	v_mov_b32_e32 v163, v147
	v_lshl_add_u64 v[170:171], v[160:161], 0, v[162:163]
	s_waitcnt vmcnt(0) lgkmcnt(0)
	s_barrier
	v_mov_b32_e32 v160, v200
	v_mov_b32_e32 v161, v201
	v_mov_b32_e32 v162, v202
	v_mov_b32_e32 v163, v203
	v_mov_b32_e32 v176, v204
	v_mov_b32_e32 v177, v205
	v_mov_b32_e32 v178, v206
	v_mov_b32_e32 v179, v207
	s_mov_b32 s14, 0x358637bd
	s_lshl_b32 s70, s70, 3
	v_lshl_add_u64 v[170:171], v[170:171], 0, s[70:71]
	s_waitcnt vmcnt(1)
	v_pk_mul_f32 v[162:163], s[30:31], v[162:163] op_sel_hi:[0,1]
	s_waitcnt vmcnt(0)
	v_pk_mul_f32 v[166:167], v[176:177], s[30:31] op_sel_hi:[1,0]
	ds_read2_b32 v[176:177], v211 offset1:16
	v_pk_mul_f32 v[164:165], v[178:179], s[30:31] op_sel_hi:[1,0]
	v_pk_mul_f32 v[160:161], s[30:31], v[160:161] op_sel_hi:[0,1]
	s_waitcnt lgkmcnt(0)
	v_pk_add_f32 v[176:177], v[132:133], v[176:177]
	v_mov_b64_e32 v[132:133], s[14:15]
	v_pk_fma_f32 v[176:177], v[176:177], s[8:9], v[132:133] op_sel_hi:[1,0,0]
	s_nop 0
	v_mul_f32_e32 v157, 0x4b800000, v176
	v_cmp_gt_f32_e64 s[42:43], s11, v176
	v_cmp_gt_f32_e32 vcc, s11, v177
	s_nop 0
	v_cndmask_b32_e64 v157, v176, v157, s[42:43]
	v_rsq_f32_e32 v176, v157
	v_mul_f32_e32 v157, 0x4b800000, v177
	v_cndmask_b32_e32 v157, v177, v157, vcc
	v_rsq_f32_e32 v177, v157
	s_nop 0
	v_pk_mul_f32 v[178:179], v[176:177], s[10:11] op_sel_hi:[1,0]
	s_nop 0
	v_cndmask_b32_e64 v190, v176, v178, s[42:43]
	v_cndmask_b32_e32 v191, v177, v179, vcc
	ds_read2_b32 v[176:177], v211 offset0:32 offset1:48
	s_waitcnt lgkmcnt(0)
	v_pk_add_f32 v[168:169], v[168:169], v[176:177]
	s_nop 0
	v_pk_fma_f32 v[168:169], v[168:169], s[8:9], v[132:133] op_sel_hi:[1,0,0]
	s_nop 0
	v_mul_f32_e32 v157, 0x4b800000, v168
	v_cmp_gt_f32_e64 s[42:43], s11, v168
	v_cmp_gt_f32_e32 vcc, s11, v169
	s_nop 0
	v_cndmask_b32_e64 v157, v168, v157, s[42:43]
	v_rsq_f32_e32 v168, v157
	v_mul_f32_e32 v157, 0x4b800000, v169
	v_cndmask_b32_e32 v157, v169, v157, vcc
	v_rsq_f32_e32 v169, v157
	s_nop 0
	v_pk_mul_f32 v[176:177], v[168:169], s[10:11] op_sel_hi:[1,0]
	s_nop 0
	v_cndmask_b32_e64 v186, v168, v176, s[42:43]
	v_cndmask_b32_e32 v187, v169, v177, vcc
	ds_read_b32 v168, v212
	ds_read2_b32 v[176:177], v211 offset0:80 offset1:96
	ds_read2_b32 v[178:179], v211 offset0:112 offset1:144
	s_waitcnt lgkmcnt(1)
	v_mov_b32_e32 v169, v176
	v_pk_add_f32 v[168:169], v[172:173], v[168:169]
	s_nop 0
	v_pk_fma_f32 v[168:169], v[168:169], s[8:9], v[132:133] op_sel_hi:[1,0,0]
	s_nop 0
	v_mul_f32_e32 v157, 0x4b800000, v168
	v_cmp_gt_f32_e64 s[42:43], s11, v168
	v_cmp_gt_f32_e32 vcc, s11, v169
	s_nop 0
	v_cndmask_b32_e64 v157, v168, v157, s[42:43]
	v_rsq_f32_e32 v168, v157
	v_mul_f32_e32 v157, 0x4b800000, v169
	v_cndmask_b32_e32 v157, v169, v157, vcc
	v_rsq_f32_e32 v169, v157
	s_nop 0
	v_pk_mul_f32 v[172:173], v[168:169], s[10:11] op_sel_hi:[1,0]
	s_nop 0
	v_cndmask_b32_e64 v182, v168, v172, s[42:43]
	v_cndmask_b32_e32 v183, v169, v173, vcc
	v_mov_b32_e32 v168, v177
	s_waitcnt lgkmcnt(0)
	v_mov_b32_e32 v169, v178
	v_pk_add_f32 v[168:169], v[174:175], v[168:169]
	s_nop 0
	v_pk_fma_f32 v[168:169], v[168:169], s[8:9], v[132:133] op_sel_hi:[1,0,0]
	s_nop 0
	v_mul_f32_e32 v157, 0x4b800000, v168
	v_cmp_gt_f32_e64 s[42:43], s11, v168
	v_cmp_gt_f32_e32 vcc, s11, v169
	s_nop 0
	v_cndmask_b32_e64 v157, v168, v157, s[42:43]
	v_rsq_f32_e32 v168, v157
	v_mul_f32_e32 v157, 0x4b800000, v169
	v_cndmask_b32_e32 v157, v169, v157, vcc
	v_rsq_f32_e32 v169, v157
	s_nop 0
	v_pk_mul_f32 v[172:173], v[168:169], s[10:11] op_sel_hi:[1,0]
	s_nop 0
	v_cndmask_b32_e64 v168, v168, v172, s[42:43]
	v_cndmask_b32_e32 v169, v169, v173, vcc
	v_mov_b32_e32 v192, v216
	v_mov_b32_e32 v193, v217
	v_mov_b32_e32 v194, v218
	v_mov_b32_e32 v195, v219
	s_nop 0
	v_mov_b32_e32 v170, v224
	v_mov_b32_e32 v171, v225
	v_mov_b32_e32 v172, v226
	v_mov_b32_e32 v173, v227
	ds_read_b32 v178, v213
	s_waitcnt lgkmcnt(0)
	v_pk_add_f32 v[136:137], v[136:137], v[178:179]
	s_nop 0
	v_pk_fma_f32 v[136:137], v[136:137], s[8:9], v[132:133] op_sel_hi:[1,0,0]
	s_waitcnt vmcnt(1)
	v_pk_mul_f32 v[176:177], s[30:31], v[192:193] op_sel_hi:[0,1]
	v_mul_f32_e32 v157, 0x4b800000, v136
	v_cmp_gt_f32_e64 s[42:43], s11, v136
	v_cmp_gt_f32_e32 vcc, s11, v137
	s_waitcnt vmcnt(0)
	v_pk_mul_f32 v[174:175], s[30:31], v[172:173] op_sel_hi:[0,1]
	v_cndmask_b32_e64 v136, v136, v157, s[42:43]
	v_mul_f32_e32 v157, 0x4b800000, v137
	v_cndmask_b32_e32 v137, v137, v157, vcc
	v_rsq_f32_e32 v136, v136
	v_rsq_f32_e32 v137, v137
	v_pk_mul_f32 v[172:173], s[30:31], v[170:171] op_sel_hi:[0,1]
	v_pk_mul_f32 v[170:171], s[30:31], v[194:195] op_sel_hi:[0,1]
	v_pk_mul_f32 v[178:179], v[136:137], s[10:11] op_sel_hi:[1,0]
	s_nop 0
	v_cndmask_b32_e64 v192, v136, v178, s[42:43]
	v_cndmask_b32_e32 v193, v137, v179, vcc
	ds_read2_b32 v[136:137], v211 offset0:160 offset1:176
	s_waitcnt lgkmcnt(0)
	v_pk_add_f32 v[136:137], v[158:159], v[136:137]
	s_nop 0
	v_pk_fma_f32 v[136:137], v[136:137], s[8:9], v[132:133] op_sel_hi:[1,0,0]
	s_nop 0
	v_mul_f32_e32 v157, 0x4b800000, v136
	v_cmp_gt_f32_e64 s[42:43], s11, v136
	v_cmp_gt_f32_e32 vcc, s11, v137
	s_nop 0
	v_cndmask_b32_e64 v136, v136, v157, s[42:43]
	v_mul_f32_e32 v157, 0x4b800000, v137
	v_cndmask_b32_e32 v137, v137, v157, vcc
	v_rsq_f32_e32 v136, v136
	v_rsq_f32_e32 v137, v137
	s_nop 0
	v_pk_mul_f32 v[158:159], v[136:137], s[10:11] op_sel_hi:[1,0]
	s_nop 0
	v_cndmask_b32_e64 v188, v136, v158, s[42:43]
	v_cndmask_b32_e32 v189, v137, v159, vcc
	ds_read_b32 v158, v214
	ds_read2_b32 v[136:137], v211 offset0:208 offset1:224
	s_waitcnt lgkmcnt(0)
	v_mov_b32_e32 v159, v136
	v_pk_add_f32 v[134:135], v[134:135], v[158:159]
	s_nop 0
	v_pk_fma_f32 v[134:135], v[134:135], s[8:9], v[132:133] op_sel_hi:[1,0,0]
	s_nop 0
	v_mul_f32_e32 v136, 0x4b800000, v134
	v_cmp_gt_f32_e64 s[42:43], s11, v134
	v_cmp_gt_f32_e32 vcc, s11, v135
	s_nop 0
	v_cndmask_b32_e64 v134, v134, v136, s[42:43]
	v_mul_f32_e32 v136, 0x4b800000, v135
	v_cndmask_b32_e32 v135, v135, v136, vcc
	v_rsq_f32_e32 v134, v134
	v_rsq_f32_e32 v135, v135
	s_nop 0
	v_pk_mul_f32 v[158:159], v[134:135], s[10:11] op_sel_hi:[1,0]
	s_nop 0
	v_cndmask_b32_e32 v185, v135, v159, vcc
	ds_read_b32 v135, v215
	v_cndmask_b32_e64 v184, v134, v158, s[42:43]
	v_mov_b32_e32 v134, v137
	s_waitcnt lgkmcnt(0)
	v_pk_add_f32 v[130:131], v[130:131], v[134:135]
	s_nop 0
	v_pk_fma_f32 v[130:131], v[130:131], s[8:9], v[132:133] op_sel_hi:[1,0,0]
	s_nop 0
	v_mul_f32_e32 v132, 0x4b800000, v130
	v_cmp_gt_f32_e64 s[42:43], s11, v130
	v_cmp_gt_f32_e32 vcc, s11, v131
	s_nop 0
	v_cndmask_b32_e64 v130, v130, v132, s[42:43]
	v_mul_f32_e32 v132, 0x4b800000, v131
	v_cndmask_b32_e32 v131, v131, v132, vcc
	v_rsq_f32_e32 v130, v130
	v_rsq_f32_e32 v131, v131
	s_nop 0
	v_pk_mul_f32 v[132:133], v[130:131], s[10:11] op_sel_hi:[1,0]
	s_nop 0
	v_cndmask_b32_e64 v180, v130, v132, s[42:43]
	v_cndmask_b32_e32 v181, v131, v133, vcc
